# K-loop counted waits relaxed: vmcnt(8) at the end of phases 1,3,5,7 only (was vmcnt(6) at 2,4,6,8): each LDS-DMA gets 4-5 phases to land; epilogue store acks are not forced until phase 5 of a tile's f
# baseline (speedup 1.0000x reference)
.LBB0_386:
	s_add_i32 m0, s98, 0xc000
	ds_read_b128 v[176:179], v229 offset:2048
	ds_read_b128 v[180:183], v229 offset:3072
	ds_read_b128 v[184:187], v229 offset:4096
	ds_read_b128 v[188:191], v229 offset:5120
	ds_read_b128 v[192:195], v229 offset:6144
	ds_read_b128 v[196:199], v229 offset:7168
	global_load_lds_dwordx4 v172, s[0:1]
	s_add_i32 m0, s98, 0xe000
	s_nop 0
	global_load_lds_dwordx4 v174, s[0:1]
	s_waitcnt vmcnt(8) lgkmcnt(6)
	s_barrier
	s_waitcnt lgkmcnt(0)
	v_mfma_f32_16x16x32_bf16 v[126:129], v[130:133], v[146:149], v[126:129]
	v_mfma_f32_16x16x32_bf16 v[122:125], v[138:141], v[146:149], v[122:125]
	v_mfma_f32_16x16x32_bf16 v[110:113], v[130:133], v[176:179], v[110:113]
	v_mfma_f32_16x16x32_bf16 v[106:109], v[138:141], v[176:179], v[106:109]
	v_mfma_f32_16x16x32_bf16 v[94:97], v[130:133], v[184:187], v[94:97]
	v_mfma_f32_16x16x32_bf16 v[90:93], v[138:141], v[184:187], v[90:93]
	v_mfma_f32_16x16x32_bf16 v[78:81], v[130:133], v[192:195], v[78:81]
	v_mfma_f32_16x16x32_bf16 v[74:77], v[138:141], v[192:195], v[74:77]
	v_mfma_f32_16x16x32_bf16 v[126:129], v[134:137], v[150:153], v[126:129]
	v_mfma_f32_16x16x32_bf16 v[122:125], v[142:145], v[150:153], v[122:125]
	v_mfma_f32_16x16x32_bf16 v[110:113], v[134:137], v[180:183], v[110:113]
	v_mfma_f32_16x16x32_bf16 v[106:109], v[142:145], v[180:183], v[106:109]
	v_mfma_f32_16x16x32_bf16 v[94:97], v[134:137], v[188:191], v[94:97]
	v_mfma_f32_16x16x32_bf16 v[90:93], v[142:145], v[188:191], v[90:93]
	v_mfma_f32_16x16x32_bf16 v[78:81], v[134:137], v[196:199], v[78:81]
	v_mfma_f32_16x16x32_bf16 v[74:77], v[142:145], v[196:199], v[74:77]
	s_barrier
	v_add_u32_e32 v0, 0x14000, v224
	s_add_i32 vcc_lo, s97, 0x10000
	s_mov_b32 m0, vcc_lo
	ds_read_b128 v[200:203], v0
	ds_read_b128 v[230:233], v0 offset:1024
	ds_read_b128 v[234:237], v0 offset:2048
	ds_read_b128 v[238:241], v0 offset:3072
	ds_read_b128 v[242:245], v229 offset:16384
	ds_read_b128 v[246:249], v229 offset:17408
	global_load_lds_dwordx4 v158, s[46:47]
	s_add_i32 m0, vcc_lo, 0x2000
	s_nop 0
	global_load_lds_dwordx4 v162, s[46:47]
	s_barrier
	s_waitcnt lgkmcnt(0)
	v_mfma_f32_16x16x32_bf16 v[118:121], v[200:203], v[146:149], v[118:121]
	v_mfma_f32_16x16x32_bf16 v[114:117], v[234:237], v[146:149], v[114:117]
	v_mfma_f32_16x16x32_bf16 v[102:105], v[200:203], v[176:179], v[102:105]
	v_mfma_f32_16x16x32_bf16 v[98:101], v[234:237], v[176:179], v[98:101]
	v_mfma_f32_16x16x32_bf16 v[86:89], v[200:203], v[184:187], v[86:89]
	v_mfma_f32_16x16x32_bf16 v[82:85], v[234:237], v[184:187], v[82:85]
	v_mfma_f32_16x16x32_bf16 v[70:73], v[200:203], v[192:195], v[70:73]
	v_mfma_f32_16x16x32_bf16 v[66:69], v[234:237], v[192:195], v[66:69]
	v_mfma_f32_16x16x32_bf16 v[118:121], v[230:233], v[150:153], v[118:121]
	v_mfma_f32_16x16x32_bf16 v[114:117], v[238:241], v[150:153], v[114:117]
	v_mfma_f32_16x16x32_bf16 v[102:105], v[230:233], v[180:183], v[102:105]
	v_mfma_f32_16x16x32_bf16 v[98:101], v[238:241], v[180:183], v[98:101]
	v_mfma_f32_16x16x32_bf16 v[86:89], v[230:233], v[188:191], v[86:89]
	v_mfma_f32_16x16x32_bf16 v[82:85], v[238:241], v[188:191], v[82:85]
	v_mfma_f32_16x16x32_bf16 v[70:73], v[230:233], v[196:199], v[70:73]
	v_mfma_f32_16x16x32_bf16 v[66:69], v[238:241], v[196:199], v[66:69]
	s_barrier
	s_mov_b32 m0, s98
	ds_read_b128 v[176:179], v229 offset:18432
	ds_read_b128 v[180:183], v229 offset:19456
	ds_read_b128 v[184:187], v229 offset:20480
	ds_read_b128 v[188:191], v229 offset:21504
	ds_read_b128 v[192:195], v229 offset:22528
	ds_read_b128 v[196:199], v229 offset:23552
	global_load_lds_dwordx4 v156, s[44:45]
	s_mov_b32 m0, s99
	s_add_u32 s46, s46, s95
	global_load_lds_dwordx4 v160, s[44:45]
	s_addc_u32 s47, s47, 0
	s_waitcnt vmcnt(8)
	s_barrier
	s_waitcnt lgkmcnt(0)
	v_mfma_f32_16x16x32_bf16 v[62:65], v[130:133], v[242:245], v[62:65]
	v_mfma_f32_16x16x32_bf16 v[58:61], v[138:141], v[242:245], v[58:61]
	v_mfma_f32_16x16x32_bf16 v[46:49], v[130:133], v[176:179], v[46:49]
	v_mfma_f32_16x16x32_bf16 v[42:45], v[138:141], v[176:179], v[42:45]
	v_mfma_f32_16x16x32_bf16 v[30:33], v[130:133], v[184:187], v[30:33]
	v_mfma_f32_16x16x32_bf16 v[26:29], v[138:141], v[184:187], v[26:29]
	v_mfma_f32_16x16x32_bf16 v[14:17], v[130:133], v[192:195], v[14:17]
	v_mfma_f32_16x16x32_bf16 v[10:13], v[138:141], v[192:195], v[10:13]
	v_mfma_f32_16x16x32_bf16 v[62:65], v[134:137], v[246:249], v[62:65]
	v_mfma_f32_16x16x32_bf16 v[58:61], v[142:145], v[246:249], v[58:61]
	v_mfma_f32_16x16x32_bf16 v[46:49], v[134:137], v[180:183], v[46:49]
	v_mfma_f32_16x16x32_bf16 v[42:45], v[142:145], v[180:183], v[42:45]
	v_mfma_f32_16x16x32_bf16 v[30:33], v[134:137], v[188:191], v[30:33]
	v_mfma_f32_16x16x32_bf16 v[26:29], v[142:145], v[188:191], v[26:29]
	v_mfma_f32_16x16x32_bf16 v[14:17], v[134:137], v[196:199], v[14:17]
	v_mfma_f32_16x16x32_bf16 v[10:13], v[142:145], v[196:199], v[10:13]
	s_barrier
	s_add_i32 vcc_lo, s97, 0x14000
	s_add_i32 vcc_hi, s97, 0x16000
	s_mov_b32 m0, vcc_lo
	s_add_u32 s44, s44, s20
	global_load_lds_dwordx4 v158, s[46:47]
	s_mov_b32 m0, vcc_hi
	s_addc_u32 s45, s45, 0
	global_load_lds_dwordx4 v162, s[46:47]
	v_add_u32_e32 v0, 0x18000, v224
	ds_read_b128 v[130:133], v0
	ds_read_b128 v[134:137], v0 offset:1024
	ds_read_b128 v[138:141], v0 offset:2048
	ds_read_b128 v[142:145], v0 offset:3072
	ds_read_b128 v[146:149], v229 offset:32768
	ds_read_b128 v[150:153], v229 offset:33792
	s_barrier
	v_mfma_f32_16x16x32_bf16 v[54:57], v[200:203], v[242:245], v[54:57]
	v_mfma_f32_16x16x32_bf16 v[50:53], v[234:237], v[242:245], v[50:53]
	v_mfma_f32_16x16x32_bf16 v[38:41], v[200:203], v[176:179], v[38:41]
	v_mfma_f32_16x16x32_bf16 v[34:37], v[234:237], v[176:179], v[34:37]
	v_mfma_f32_16x16x32_bf16 v[22:25], v[200:203], v[184:187], v[22:25]
	v_mfma_f32_16x16x32_bf16 v[18:21], v[234:237], v[184:187], v[18:21]
	v_mfma_f32_16x16x32_bf16 v[6:9], v[200:203], v[192:195], v[6:9]
	v_mfma_f32_16x16x32_bf16 v[2:5], v[234:237], v[192:195], v[2:5]
	v_mfma_f32_16x16x32_bf16 v[54:57], v[230:233], v[246:249], v[54:57]
	v_mfma_f32_16x16x32_bf16 v[50:53], v[238:241], v[246:249], v[50:53]
	v_mfma_f32_16x16x32_bf16 v[38:41], v[230:233], v[180:183], v[38:41]
	v_mfma_f32_16x16x32_bf16 v[34:37], v[238:241], v[180:183], v[34:37]
	v_mfma_f32_16x16x32_bf16 v[22:25], v[230:233], v[188:191], v[22:25]
	v_mfma_f32_16x16x32_bf16 v[18:21], v[238:241], v[188:191], v[18:21]
	v_mfma_f32_16x16x32_bf16 v[6:9], v[230:233], v[196:199], v[6:9]
	v_mfma_f32_16x16x32_bf16 v[2:5], v[238:241], v[196:199], v[2:5]
	s_barrier
	s_mov_b32 m0, s94
	ds_read_b128 v[176:179], v229 offset:34816
	ds_read_b128 v[180:183], v229 offset:35840
	ds_read_b128 v[184:187], v229 offset:36864
	ds_read_b128 v[188:191], v229 offset:37888
	ds_read_b128 v[192:195], v229 offset:38912
	ds_read_b128 v[196:199], v229 offset:39936
	global_load_lds_dwordx4 v156, s[44:45]
	s_mov_b32 m0, s65
	s_nop 0
	global_load_lds_dwordx4 v160, s[44:45]
	s_waitcnt vmcnt(8) lgkmcnt(6)
	s_barrier
	s_waitcnt lgkmcnt(0)
	v_mfma_f32_16x16x32_bf16 v[126:129], v[130:133], v[146:149], v[126:129]
	v_mfma_f32_16x16x32_bf16 v[122:125], v[138:141], v[146:149], v[122:125]
	v_mfma_f32_16x16x32_bf16 v[110:113], v[130:133], v[176:179], v[110:113]
	v_mfma_f32_16x16x32_bf16 v[106:109], v[138:141], v[176:179], v[106:109]
	v_mfma_f32_16x16x32_bf16 v[94:97], v[130:133], v[184:187], v[94:97]
	v_mfma_f32_16x16x32_bf16 v[90:93], v[138:141], v[184:187], v[90:93]
	v_mfma_f32_16x16x32_bf16 v[78:81], v[130:133], v[192:195], v[78:81]
	v_mfma_f32_16x16x32_bf16 v[74:77], v[138:141], v[192:195], v[74:77]
	v_mfma_f32_16x16x32_bf16 v[126:129], v[134:137], v[150:153], v[126:129]
	v_mfma_f32_16x16x32_bf16 v[122:125], v[142:145], v[150:153], v[122:125]
	v_mfma_f32_16x16x32_bf16 v[110:113], v[134:137], v[180:183], v[110:113]
	v_mfma_f32_16x16x32_bf16 v[106:109], v[142:145], v[180:183], v[106:109]
	v_mfma_f32_16x16x32_bf16 v[94:97], v[134:137], v[188:191], v[94:97]
	v_mfma_f32_16x16x32_bf16 v[90:93], v[142:145], v[188:191], v[90:93]
	v_mfma_f32_16x16x32_bf16 v[78:81], v[134:137], v[196:199], v[78:81]
	v_mfma_f32_16x16x32_bf16 v[74:77], v[142:145], v[196:199], v[74:77]
	s_barrier
	s_sub_u32 s46, s46, s95
	s_subb_u32 s47, s47, 0
	v_add_u32_e32 v0, 0x1c000, v224
	s_add_i32 vcc_lo, s97, 0x17f80
	s_add_i32 vcc_hi, s97, 0x19f80
	s_mov_b32 m0, vcc_lo
	ds_read_b128 v[200:203], v0
	ds_read_b128 v[230:233], v0 offset:1024
	ds_read_b128 v[234:237], v0 offset:2048
	ds_read_b128 v[238:241], v0 offset:3072
	ds_read_b128 v[242:245], v229 offset:49152
	ds_read_b128 v[246:249], v229 offset:50176
	global_load_lds_dwordx4 v158, s[46:47] offset:128
	s_mov_b32 m0, vcc_hi
	s_sub_u32 s44, s44, s20
	global_load_lds_dwordx4 v162, s[46:47] offset:128
	s_subb_u32 s45, s45, 0
	s_barrier
	s_waitcnt lgkmcnt(0)
	v_mfma_f32_16x16x32_bf16 v[118:121], v[200:203], v[146:149], v[118:121]
	v_mfma_f32_16x16x32_bf16 v[114:117], v[234:237], v[146:149], v[114:117]
	v_mfma_f32_16x16x32_bf16 v[102:105], v[200:203], v[176:179], v[102:105]
	v_mfma_f32_16x16x32_bf16 v[98:101], v[234:237], v[176:179], v[98:101]
	v_mfma_f32_16x16x32_bf16 v[86:89], v[200:203], v[184:187], v[86:89]
	v_mfma_f32_16x16x32_bf16 v[82:85], v[234:237], v[184:187], v[82:85]
	v_mfma_f32_16x16x32_bf16 v[70:73], v[200:203], v[192:195], v[70:73]
	v_mfma_f32_16x16x32_bf16 v[66:69], v[234:237], v[192:195], v[66:69]
	v_mfma_f32_16x16x32_bf16 v[118:121], v[230:233], v[150:153], v[118:121]
	v_mfma_f32_16x16x32_bf16 v[114:117], v[238:241], v[150:153], v[114:117]
	v_mfma_f32_16x16x32_bf16 v[102:105], v[230:233], v[180:183], v[102:105]
	v_mfma_f32_16x16x32_bf16 v[98:101], v[238:241], v[180:183], v[98:101]
	v_mfma_f32_16x16x32_bf16 v[86:89], v[230:233], v[188:191], v[86:89]
	v_mfma_f32_16x16x32_bf16 v[82:85], v[238:241], v[188:191], v[82:85]
	v_mfma_f32_16x16x32_bf16 v[70:73], v[230:233], v[196:199], v[70:73]
	v_mfma_f32_16x16x32_bf16 v[66:69], v[238:241], v[196:199], v[66:69]
	s_barrier
	s_add_i32 m0, s87, 0xffffff80
	ds_read_b128 v[176:179], v229 offset:51200
	ds_read_b128 v[180:183], v229 offset:52224
	ds_read_b128 v[184:187], v229 offset:53248
	ds_read_b128 v[188:191], v229 offset:54272
	ds_read_b128 v[192:195], v229 offset:55296
	ds_read_b128 v[196:199], v229 offset:56320
	global_load_lds_dwordx4 v156, s[44:45] offset:128
	s_add_i32 m0, s29, 0xffffff80
	s_add_u32 s46, s46, s95
	global_load_lds_dwordx4 v160, s[44:45] offset:128
	s_addc_u32 s47, s47, 0
	s_waitcnt vmcnt(8)
	s_barrier
	s_waitcnt lgkmcnt(0)
	v_mfma_f32_16x16x32_bf16 v[62:65], v[130:133], v[242:245], v[62:65]
	v_mfma_f32_16x16x32_bf16 v[58:61], v[138:141], v[242:245], v[58:61]
	v_mfma_f32_16x16x32_bf16 v[46:49], v[130:133], v[176:179], v[46:49]
	v_mfma_f32_16x16x32_bf16 v[42:45], v[138:141], v[176:179], v[42:45]
	v_mfma_f32_16x16x32_bf16 v[30:33], v[130:133], v[184:187], v[30:33]
	v_mfma_f32_16x16x32_bf16 v[26:29], v[138:141], v[184:187], v[26:29]
	v_mfma_f32_16x16x32_bf16 v[14:17], v[130:133], v[192:195], v[14:17]
	v_mfma_f32_16x16x32_bf16 v[10:13], v[138:141], v[192:195], v[10:13]
	v_mfma_f32_16x16x32_bf16 v[62:65], v[134:137], v[246:249], v[62:65]
	v_mfma_f32_16x16x32_bf16 v[58:61], v[142:145], v[246:249], v[58:61]
	v_mfma_f32_16x16x32_bf16 v[46:49], v[134:137], v[180:183], v[46:49]
	v_mfma_f32_16x16x32_bf16 v[42:45], v[142:145], v[180:183], v[42:45]
	v_mfma_f32_16x16x32_bf16 v[30:33], v[134:137], v[188:191], v[30:33]
	v_mfma_f32_16x16x32_bf16 v[26:29], v[142:145], v[188:191], v[26:29]
	v_mfma_f32_16x16x32_bf16 v[14:17], v[134:137], v[196:199], v[14:17]
	v_mfma_f32_16x16x32_bf16 v[10:13], v[142:145], v[196:199], v[10:13]
	s_barrier
	s_add_i32 vcc_lo, s97, 0x1bf80
	s_add_i32 vcc_hi, s97, 0x1df80
	s_mov_b32 m0, vcc_lo
	s_add_u32 s0, s0, 0x100
	global_load_lds_dwordx4 v158, s[46:47] offset:128
	s_mov_b32 m0, vcc_hi
	s_addc_u32 s1, s1, 0
	global_load_lds_dwordx4 v162, s[46:47] offset:128
	v_add_u32_e32 v0, 0x10000, v224
	ds_read_b128 v[130:133], v0
	ds_read_b128 v[134:137], v0 offset:1024
	ds_read_b128 v[138:141], v0 offset:2048
	ds_read_b128 v[142:145], v0 offset:3072
	ds_read_b128 v[146:149], v229
	ds_read_b128 v[150:153], v229 offset:1024
	s_add_u32 s48, s48, 0x100
	s_addc_u32 s49, s49, 0
	s_cmp_ge_i32 s71, s6
	s_cselect_b64 vcc, -1, 0
	s_mov_b32 s44, s71
	s_add_i32 s71, s44, 2
	s_add_u32 s46, s0, 0x80
	s_addc_u32 s45, s1, 0
	s_cmp_eq_u32 s43, s44
	s_cselect_b32 s44, s72, s46
	s_cselect_b32 s45, s73, s45
	s_cselect_b32 s47, s75, s49
	s_cselect_b32 s46, s74, s48
	s_barrier
	v_mfma_f32_16x16x32_bf16 v[54:57], v[200:203], v[242:245], v[54:57]
	v_mfma_f32_16x16x32_bf16 v[50:53], v[234:237], v[242:245], v[50:53]
	v_mfma_f32_16x16x32_bf16 v[38:41], v[200:203], v[176:179], v[38:41]
	v_mfma_f32_16x16x32_bf16 v[34:37], v[234:237], v[176:179], v[34:37]
	v_mfma_f32_16x16x32_bf16 v[22:25], v[200:203], v[184:187], v[22:25]
	v_mfma_f32_16x16x32_bf16 v[18:21], v[234:237], v[184:187], v[18:21]
	v_mfma_f32_16x16x32_bf16 v[6:9], v[200:203], v[192:195], v[6:9]
	v_mfma_f32_16x16x32_bf16 v[2:5], v[234:237], v[192:195], v[2:5]
	v_mfma_f32_16x16x32_bf16 v[54:57], v[230:233], v[246:249], v[54:57]
	v_mfma_f32_16x16x32_bf16 v[50:53], v[238:241], v[246:249], v[50:53]
	v_mfma_f32_16x16x32_bf16 v[38:41], v[230:233], v[180:183], v[38:41]
	v_mfma_f32_16x16x32_bf16 v[34:37], v[238:241], v[180:183], v[34:37]
	v_mfma_f32_16x16x32_bf16 v[22:25], v[230:233], v[188:191], v[22:25]
	v_mfma_f32_16x16x32_bf16 v[18:21], v[238:241], v[188:191], v[18:21]
	v_mfma_f32_16x16x32_bf16 v[6:9], v[230:233], v[196:199], v[6:9]
	v_mfma_f32_16x16x32_bf16 v[2:5], v[238:241], v[196:199], v[2:5]
	s_barrier
	s_cbranch_vccz .LBB0_386
	s_waitcnt lgkmcnt(0)
	s_lshl_b32 s46, s77, 8
	s_cmp_lt_i32 s64, 1
	s_mov_b64 s[0:1], -1
	s_cbranch_scc1 .LBB0_403
